# speedup vs baseline: 1.0209x; 1.0114x over previous
; __global__ void __launch_bounds__(NWAVES * 64) fwd_mega(Params p) {
;     ...
;         for (int it = gw; it < DEPTH * I_LAYER; it += NGW) {
;             const int L = it / I_LAYER; int r = it % I_LAYER; unsigned char* wl = ws + WS_W + (size_t)L * W_LAYER;
;             if (r < I_IN) { convert_item(p.w_in + (size_t)L * D * NQKV, p.attn_norm + L * D, D, NQKV, (bf16*)(wl + W_IN), 32 * (r / 12), 256 * (r % 12), (L & 1) ? 3 : 0, lane); continue; } r -= I_IN;
;             if (r < I_OUT) { convert_item(p.w_out + (size_t)L * D * D, nullptr, D, D, (bf16*)(wl + W_OUT), 32 * (r / 4), 256 * (r % 4), 0, lane); continue; } r -= I_OUT;
;             if (r < 2 * I_G) { const int up = r / I_G; r %= I_G; convert_item((up ? p.w_up : p.w_gate) + (size_t)L * D * FF, p.ffn_norm + L * D, D, FF, (bf16*)(wl + W_GU), 32 * (r / 11), 256 * (r % 11), 1 + up, lane); continue; } r -= 2 * I_G;
;             convert_item(p.w_down + (size_t)L * FF * D, nullptr, FF, D, (bf16*)(wl + W_DN), 32 * (r / 4), 256 * (r % 4), 0, lane);
.LBB0_15:
	s_add_i32 s62, s62, s35
	s_cmpk_lt_i32 s62, 0x1800
	s_cbranch_scc1 .Lpro_norm
	s_cmpk_gt_i32 s62, 0x1fff
	s_cbranch_scc1 .LBB0_97
	s_and_b32 s0, s34, 7
	s_mul_i32 s0, s0, s33
	s_lshr_b32 s1, s34, 3
	s_add_i32 s0, s0, s1
	s_addk_i32 s0, 0x1800
	s_mov_b32 s62, s0
.Lpro_norm:
	s_cmpk_gt_i32 s62, 0x187f
	s_cbranch_scc1 .LBB0_97

; __device__ __forceinline__ unsigned cvt_pk_bf16(float lo, float hi) { unsigned r; asm volatile("v_cvt_pk_bf16_f32 %0, %1, %2" : "=v"(r) : "v"(lo), "v"(hi)); return r; }
;     __device__ __forceinline__ void operator()(const f32x4 (&acc)[2][2][4][2], const Unit& u, int wr, int wc, int fr, int fq) const {
;     ...
;             for (int m = 0; m < 4; ++m) { const int row = row0 + ai * HALF + m * 16; const float rs = __builtin_amdgcn_rsqf((float)sq[ai][m] * (1.0f / (1024.0f * 1048576.0f)) + RMS_EPS) * sc;
;     __device__ __forceinline__ void operator()(const f32x4 (&acc)[2][2][4][2], const Unit& u, int wr, int wc, int fr, int fq) const {
;         const int row0 = u.pm * BM + wr * 64 + fr; const int col0 = u.pn * HALF + wc * 32 + 8 * fq;
;         unsigned long long sq[2][4];
; #pragma unroll
;         for (int ai = 0; ai < 2; ++ai)
; #pragma unroll
;             for (int m = 0; m < 4; ++m) sq[ai][m] = ssq[row0 + ai * HALF + m * 16];
; #pragma unroll
;         for (int ai = 0; ai < 2; ++ai)
; #pragma unroll
;             for (int m = 0; m < 4; ++m) { const int row = row0 + ai * HALF + m * 16; const float rs = __builtin_amdgcn_rsqf((float)sq[ai][m] * (1.0f / (1024.0f * 1048576.0f)) + RMS_EPS);
;                 float hv[8];
; #pragma unroll
;                 for (int n = 0; n < 2; ++n)
; #pragma unroll
;                     for (int j = 0; j < 4; ++j) { const float g = acc[ai][0][m][n][j] * rs, uu = acc[ai][1][m][n][j] * rs;
;                         const float sg = g * __builtin_amdgcn_rcpf(1.0f + __builtin_amdgcn_exp2f(-1.4426950408889634f * g)); hv[n * 4 + j] = sg * uu; }
;                 u32x4 w; w.x = cvt_pk_bf16(hv[0], hv[1]); w.y = cvt_pk_bf16(hv[2], hv[3]); w.z = cvt_pk_bf16(hv[4], hv[5]); w.w = cvt_pk_bf16(hv[6], hv[7]);
;                 *(u32x4*)(H + (size_t)row * 2816 + col0) = w; }
.LBB0_431:
	s_nop 0
	v_lshl_add_u32 v160, s16, 8, v165
	v_ashrrev_i32_e32 v161, 31, v160
	v_lshl_add_u64 v[140:141], v[160:161], 3, s[34:35]
	global_load_dwordx2 v[170:171], v[140:141], off
	global_load_dwordx2 v[146:147], v[140:141], off offset:1024
	global_load_dwordx2 v[144:145], v[140:141], off offset:1152
	v_or_b32_e32 v156, 16, v160
	v_ashrrev_i32_e32 v157, 31, v156
	v_or_b32_e32 v152, 32, v160
	v_lshl_add_u64 v[142:143], v[156:157], 3, s[34:35]
	v_ashrrev_i32_e32 v153, 31, v152
	v_or_b32_e32 v148, 48, v160
	global_load_dwordx2 v[158:159], v[142:143], off
	v_lshl_add_u64 v[142:143], v[152:153], 3, s[34:35]
	v_ashrrev_i32_e32 v149, 31, v148
	global_load_dwordx2 v[154:155], v[142:143], off
	v_lshl_add_u64 v[142:143], v[148:149], 3, s[34:35]
	global_load_dwordx2 v[150:151], v[142:143], off
	v_lshl_or_b32 v162, s17, 7, v167
	global_load_dwordx2 v[142:143], v[140:141], off offset:1280
	v_ashrrev_i32_e32 v163, 31, v162
	global_load_dwordx2 v[140:141], v[140:141], off offset:1408
	s_movk_i32 s9, 0x1600
	v_add_u32_e32 v161, 0x80, v160
	v_add_u32_e32 v157, 0x90, v160
	v_add_u32_e32 v153, 0xa0, v160
	v_add_u32_e32 v149, 0xb0, v160
	s_andn2_b64 vcc, exec, s[4:5]
	s_waitcnt vmcnt(0)
	v_ffbh_u32_e32 v212, v171
	v_ffbh_u32_e32 v213, v159
	v_ffbh_u32_e32 v214, v155
	v_ffbh_u32_e32 v215, v151
	v_ffbh_u32_e32 v216, v147
	v_ffbh_u32_e32 v217, v145
	v_ffbh_u32_e32 v218, v143
	v_ffbh_u32_e32 v219, v141
	v_min_u32_e32 v212, 32, v212
	v_min_u32_e32 v213, 32, v213
	v_min_u32_e32 v214, 32, v214
	v_min_u32_e32 v215, 32, v215
	v_min_u32_e32 v216, 32, v216
	v_min_u32_e32 v217, 32, v217
	v_min_u32_e32 v218, 32, v218
	v_min_u32_e32 v219, 32, v219
	v_lshlrev_b64 v[196:197], v212, v[170:171]
	v_lshlrev_b64 v[198:199], v213, v[158:159]
	v_lshlrev_b64 v[200:201], v214, v[154:155]
	v_lshlrev_b64 v[202:203], v215, v[150:151]
	v_lshlrev_b64 v[204:205], v216, v[146:147]
	v_lshlrev_b64 v[206:207], v217, v[144:145]
	v_lshlrev_b64 v[208:209], v218, v[142:143]
	v_lshlrev_b64 v[210:211], v219, v[140:141]
	v_min_u32_e32 v196, 1, v196
	v_min_u32_e32 v198, 1, v198
	v_min_u32_e32 v200, 1, v200
	v_min_u32_e32 v202, 1, v202
	v_min_u32_e32 v204, 1, v204
	v_min_u32_e32 v206, 1, v206
	v_min_u32_e32 v208, 1, v208
	v_min_u32_e32 v210, 1, v210
	v_or_b32_e32 v196, v197, v196
	v_or_b32_e32 v198, v199, v198
	v_or_b32_e32 v200, v201, v200
	v_or_b32_e32 v202, v203, v202
	v_or_b32_e32 v204, v205, v204
	v_or_b32_e32 v206, v207, v206
	v_or_b32_e32 v208, v209, v208
	v_or_b32_e32 v210, v211, v210
	v_cvt_f32_u32_e32 v196, v196
	v_cvt_f32_u32_e32 v198, v198
	v_cvt_f32_u32_e32 v200, v200
	v_cvt_f32_u32_e32 v202, v202
	v_cvt_f32_u32_e32 v204, v204
	v_cvt_f32_u32_e32 v206, v206
	v_cvt_f32_u32_e32 v208, v208
	v_cvt_f32_u32_e32 v210, v210
	v_sub_u32_e32 v212, 32, v212
	v_sub_u32_e32 v213, 32, v213
	v_sub_u32_e32 v214, 32, v214
	v_sub_u32_e32 v215, 32, v215
	v_sub_u32_e32 v216, 32, v216
	v_sub_u32_e32 v217, 32, v217
	v_sub_u32_e32 v218, 32, v218
	v_sub_u32_e32 v219, 32, v219
	v_ldexp_f32 v196, v196, v212
	v_ldexp_f32 v198, v198, v213
	v_ldexp_f32 v200, v200, v214
	v_ldexp_f32 v202, v202, v215
	v_ldexp_f32 v204, v204, v216
	v_ldexp_f32 v206, v206, v217
	v_ldexp_f32 v208, v208, v218
	v_ldexp_f32 v210, v210, v219
	v_fmamk_f32 v196, v196, 0x30800000, v240
	v_fmamk_f32 v198, v198, 0x30800000, v240
	v_fmamk_f32 v200, v200, 0x30800000, v240
	v_fmamk_f32 v202, v202, 0x30800000, v240
	v_fmamk_f32 v204, v204, 0x30800000, v240
	v_fmamk_f32 v206, v206, 0x30800000, v240
	v_fmamk_f32 v208, v208, 0x30800000, v240
	v_fmamk_f32 v210, v210, 0x30800000, v240
	v_rsq_f32_e32 v172, v196
	v_rsq_f32_e32 v173, v198
	v_rsq_f32_e32 v174, v200
	v_rsq_f32_e32 v175, v202
	v_rsq_f32_e32 v176, v204
	v_rsq_f32_e32 v177, v206
	v_rsq_f32_e32 v178, v208
	v_rsq_f32_e32 v179, v210
	v_mov_b64_e32 v[180:181], s[56:57]
	v_lshlrev_b64 v[182:183], 1, v[162:163]
	v_mul_f32_e32 v196, v126, v172
	v_mul_f32_e32 v197, v127, v172
	v_mul_f32_e32 v198, v128, v172
	v_mul_f32_e32 v199, v129, v172
	v_mul_f32_e32 v200, v118, v172
	v_mul_f32_e32 v201, v119, v172
	v_mul_f32_e32 v202, v120, v172
	v_mul_f32_e32 v203, v121, v172
	v_mul_f32_e32 v204, v122, v172
	v_mul_f32_e32 v205, v123, v172
	v_mul_f32_e32 v206, v124, v172
	v_mul_f32_e32 v207, v125, v172
	v_mul_f32_e32 v208, v114, v172
	v_mul_f32_e32 v209, v115, v172
	v_mul_f32_e32 v210, v116, v172
	v_mul_f32_e32 v211, v117, v172
	v_mul_f32_e32 v212, 0xbfb8aa3b, v196
	v_mul_f32_e32 v213, 0xbfb8aa3b, v197
	v_mul_f32_e32 v214, 0xbfb8aa3b, v198
	v_mul_f32_e32 v215, 0xbfb8aa3b, v199
	v_mul_f32_e32 v216, 0xbfb8aa3b, v200
	v_mul_f32_e32 v217, 0xbfb8aa3b, v201
	v_mul_f32_e32 v218, 0xbfb8aa3b, v202
	v_mul_f32_e32 v219, 0xbfb8aa3b, v203
	v_exp_f32_e32 v212, v212
	v_exp_f32_e32 v213, v213
	v_exp_f32_e32 v214, v214
	v_exp_f32_e32 v215, v215
	v_exp_f32_e32 v216, v216
	v_exp_f32_e32 v217, v217
	v_exp_f32_e32 v218, v218
	v_exp_f32_e32 v219, v219
	v_add_f32_e32 v212, 1.0, v212
	v_add_f32_e32 v213, 1.0, v213
	v_add_f32_e32 v214, 1.0, v214
	v_add_f32_e32 v215, 1.0, v215
	v_add_f32_e32 v216, 1.0, v216
	v_add_f32_e32 v217, 1.0, v217
	v_add_f32_e32 v218, 1.0, v218
	v_add_f32_e32 v219, 1.0, v219
	v_rcp_f32_e32 v212, v212
	v_rcp_f32_e32 v213, v213
	v_rcp_f32_e32 v214, v214
	v_rcp_f32_e32 v215, v215
	v_rcp_f32_e32 v216, v216
	v_rcp_f32_e32 v217, v217
	v_rcp_f32_e32 v218, v218
	v_rcp_f32_e32 v219, v219
	v_mul_f32_e32 v212, v196, v212
	v_mul_f32_e32 v213, v197, v213
	v_mul_f32_e32 v214, v198, v214
	v_mul_f32_e32 v215, v199, v215
	v_mul_f32_e32 v216, v200, v216
	v_mul_f32_e32 v217, v201, v217
	v_mul_f32_e32 v218, v202, v218
	v_mul_f32_e32 v219, v203, v219
	v_mul_f32_e32 v212, v204, v212
	v_mul_f32_e32 v213, v205, v213
; __device__ __forceinline__ unsigned cvt_pk_bf16(float lo, float hi) { unsigned r; asm volatile("v_cvt_pk_bf16_f32 %0, %1, %2" : "=v"(r) : "v"(lo), "v"(hi)); return r; }
;     __device__ __forceinline__ void operator()(const f32x4 (&acc)[2][2][4][2], const Unit& u, int wr, int wc, int fr, int fq) const {
;     ...
;             for (int m = 0; m < 4; ++m) { const int row = row0 + ai * HALF + m * 16; const float rs = __builtin_amdgcn_rsqf((float)sq[ai][m] * (1.0f / (1024.0f * 1048576.0f)) + RMS_EPS);
;                 float hv[8];
; #pragma unroll
;                 for (int n = 0; n < 2; ++n)
; #pragma unroll
;                     for (int j = 0; j < 4; ++j) { const float g = acc[ai][0][m][n][j] * rs, uu = acc[ai][1][m][n][j] * rs;
;                         const float sg = g * __builtin_amdgcn_rcpf(1.0f + __builtin_amdgcn_exp2f(-1.4426950408889634f * g)); hv[n * 4 + j] = sg * uu; }
;                 u32x4 w; w.x = cvt_pk_bf16(hv[0], hv[1]); w.y = cvt_pk_bf16(hv[2], hv[3]); w.z = cvt_pk_bf16(hv[4], hv[5]); w.w = cvt_pk_bf16(hv[6], hv[7]);
;                 *(u32x4*)(H + (size_t)row * 2816 + col0) = w; }
	v_mul_f32_e32 v214, v206, v214
	v_mul_f32_e32 v215, v207, v215
	v_mul_f32_e32 v216, v208, v216
	v_mul_f32_e32 v217, v209, v217
	v_mul_f32_e32 v218, v210, v218
	v_mul_f32_e32 v219, v211, v219
	v_mad_i64_i32 v[184:185], s[16:17], v160, s9, v[180:181]
	v_cvt_pk_bf16_f32 v188, v212, v213
	v_cvt_pk_bf16_f32 v189, v214, v215
	v_cvt_pk_bf16_f32 v190, v216, v217
	v_cvt_pk_bf16_f32 v191, v218, v219
	v_lshl_add_u64 v[184:185], v[184:185], 0, v[182:183]
	global_store_dwordx4 v[184:185], v[188:191], off
	v_mul_f32_e32 v196, v110, v173
	v_mul_f32_e32 v197, v111, v173
	v_mul_f32_e32 v198, v112, v173
	v_mul_f32_e32 v199, v113, v173
	v_mul_f32_e32 v200, v102, v173
	v_mul_f32_e32 v201, v103, v173
	v_mul_f32_e32 v202, v104, v173
	v_mul_f32_e32 v203, v105, v173
	v_mul_f32_e32 v204, v106, v173
	v_mul_f32_e32 v205, v107, v173
	v_mul_f32_e32 v206, v108, v173
	v_mul_f32_e32 v207, v109, v173
	v_mul_f32_e32 v208, v98, v173
	v_mul_f32_e32 v209, v99, v173
	v_mul_f32_e32 v210, v100, v173
	v_mul_f32_e32 v211, v101, v173
	v_mul_f32_e32 v212, 0xbfb8aa3b, v196
	v_mul_f32_e32 v213, 0xbfb8aa3b, v197
	v_mul_f32_e32 v214, 0xbfb8aa3b, v198
	v_mul_f32_e32 v215, 0xbfb8aa3b, v199
	v_mul_f32_e32 v216, 0xbfb8aa3b, v200
	v_mul_f32_e32 v217, 0xbfb8aa3b, v201
	v_mul_f32_e32 v218, 0xbfb8aa3b, v202
	v_mul_f32_e32 v219, 0xbfb8aa3b, v203
	v_exp_f32_e32 v212, v212
	v_exp_f32_e32 v213, v213
	v_exp_f32_e32 v214, v214
	v_exp_f32_e32 v215, v215
	v_exp_f32_e32 v216, v216
	v_exp_f32_e32 v217, v217
	v_exp_f32_e32 v218, v218
	v_exp_f32_e32 v219, v219
	v_add_f32_e32 v212, 1.0, v212
	v_add_f32_e32 v213, 1.0, v213
	v_add_f32_e32 v214, 1.0, v214
	v_add_f32_e32 v215, 1.0, v215
	v_add_f32_e32 v216, 1.0, v216
	v_add_f32_e32 v217, 1.0, v217
	v_add_f32_e32 v218, 1.0, v218
	v_add_f32_e32 v219, 1.0, v219
	v_rcp_f32_e32 v212, v212
	v_rcp_f32_e32 v213, v213
	v_rcp_f32_e32 v214, v214
	v_rcp_f32_e32 v215, v215
	v_rcp_f32_e32 v216, v216
	v_rcp_f32_e32 v217, v217
	v_rcp_f32_e32 v218, v218
	v_rcp_f32_e32 v219, v219
	v_mul_f32_e32 v212, v196, v212
	v_mul_f32_e32 v213, v197, v213
	v_mul_f32_e32 v214, v198, v214
	v_mul_f32_e32 v215, v199, v215
	v_mul_f32_e32 v216, v200, v216
	v_mul_f32_e32 v217, v201, v217
	v_mul_f32_e32 v218, v202, v218
	v_mul_f32_e32 v219, v203, v219
	v_mul_f32_e32 v212, v204, v212
	v_mul_f32_e32 v213, v205, v213
	v_mul_f32_e32 v214, v206, v214
	v_mul_f32_e32 v215, v207, v215
	v_mul_f32_e32 v216, v208, v216
	v_mul_f32_e32 v217, v209, v217
	v_mul_f32_e32 v218, v210, v218
	v_mul_f32_e32 v219, v211, v219
	v_mad_i64_i32 v[186:187], s[16:17], v156, s9, v[180:181]
	v_cvt_pk_bf16_f32 v192, v212, v213
	v_cvt_pk_bf16_f32 v193, v214, v215
	v_cvt_pk_bf16_f32 v194, v216, v217
	v_cvt_pk_bf16_f32 v195, v218, v219
	v_lshl_add_u64 v[186:187], v[186:187], 0, v[182:183]
	global_store_dwordx4 v[186:187], v[192:195], off
	v_mul_f32_e32 v196, v94, v174
	v_mul_f32_e32 v197, v95, v174
	v_mul_f32_e32 v198, v96, v174
	v_mul_f32_e32 v199, v97, v174
	v_mul_f32_e32 v200, v86, v174
	v_mul_f32_e32 v201, v87, v174
	v_mul_f32_e32 v202, v88, v174
	v_mul_f32_e32 v203, v89, v174
	v_mul_f32_e32 v204, v90, v174
	v_mul_f32_e32 v205, v91, v174
	v_mul_f32_e32 v206, v92, v174
	v_mul_f32_e32 v207, v93, v174
	v_mul_f32_e32 v208, v82, v174
	v_mul_f32_e32 v209, v83, v174
	v_mul_f32_e32 v210, v84, v174
	v_mul_f32_e32 v211, v85, v174
	v_mul_f32_e32 v212, 0xbfb8aa3b, v196
	v_mul_f32_e32 v213, 0xbfb8aa3b, v197
	v_mul_f32_e32 v214, 0xbfb8aa3b, v198
	v_mul_f32_e32 v215, 0xbfb8aa3b, v199
	v_mul_f32_e32 v216, 0xbfb8aa3b, v200
	v_mul_f32_e32 v217, 0xbfb8aa3b, v201
	v_mul_f32_e32 v218, 0xbfb8aa3b, v202
	v_mul_f32_e32 v219, 0xbfb8aa3b, v203
	v_exp_f32_e32 v212, v212
	v_exp_f32_e32 v213, v213
	v_exp_f32_e32 v214, v214
	v_exp_f32_e32 v215, v215
	v_exp_f32_e32 v216, v216
	v_exp_f32_e32 v217, v217
	v_exp_f32_e32 v218, v218
	v_exp_f32_e32 v219, v219
	v_add_f32_e32 v212, 1.0, v212
	v_add_f32_e32 v213, 1.0, v213
	v_add_f32_e32 v214, 1.0, v214
	v_add_f32_e32 v215, 1.0, v215
	v_add_f32_e32 v216, 1.0, v216
	v_add_f32_e32 v217, 1.0, v217
	v_add_f32_e32 v218, 1.0, v218
	v_add_f32_e32 v219, 1.0, v219
	v_rcp_f32_e32 v212, v212
	v_rcp_f32_e32 v213, v213
	v_rcp_f32_e32 v214, v214
	v_rcp_f32_e32 v215, v215
	v_rcp_f32_e32 v216, v216
	v_rcp_f32_e32 v217, v217
	v_rcp_f32_e32 v218, v218
	v_rcp_f32_e32 v219, v219
	v_mul_f32_e32 v212, v196, v212
	v_mul_f32_e32 v213, v197, v213
	v_mul_f32_e32 v214, v198, v214
	v_mul_f32_e32 v215, v199, v215
	v_mul_f32_e32 v216, v200, v216
	v_mul_f32_e32 v217, v201, v217
	v_mul_f32_e32 v218, v202, v218
	v_mul_f32_e32 v219, v203, v219
	v_mul_f32_e32 v212, v204, v212
	v_mul_f32_e32 v213, v205, v213
	v_mul_f32_e32 v214, v206, v214
	v_mul_f32_e32 v215, v207, v215
	v_mul_f32_e32 v216, v208, v216
	v_mul_f32_e32 v217, v209, v217
	v_mul_f32_e32 v218, v210, v218
	v_mul_f32_e32 v219, v211, v219
	v_mad_i64_i32 v[184:185], s[16:17], v152, s9, v[180:181]
	v_cvt_pk_bf16_f32 v188, v212, v213
	v_cvt_pk_bf16_f32 v189, v214, v215
	v_cvt_pk_bf16_f32 v190, v216, v217
	v_cvt_pk_bf16_f32 v191, v218, v219
	v_lshl_add_u64 v[184:185], v[184:185], 0, v[182:183]
	global_store_dwordx4 v[184:185], v[188:191], off
	v_mul_f32_e32 v196, v78, v175
	v_mul_f32_e32 v197, v79, v175
	v_mul_f32_e32 v198, v80, v175
	v_mul_f32_e32 v199, v81, v175
	v_mul_f32_e32 v200, v70, v175
	v_mul_f32_e32 v201, v71, v175
	v_mul_f32_e32 v202, v72, v175
	v_mul_f32_e32 v203, v73, v175
	v_mul_f32_e32 v204, v74, v175
	v_mul_f32_e32 v205, v75, v175
	v_mul_f32_e32 v206, v76, v175
	v_mul_f32_e32 v207, v77, v175
	v_mul_f32_e32 v208, v66, v175
	v_mul_f32_e32 v209, v67, v175
	v_mul_f32_e32 v210, v68, v175
	v_mul_f32_e32 v211, v69, v175
	v_mul_f32_e32 v212, 0xbfb8aa3b, v196
	v_mul_f32_e32 v213, 0xbfb8aa3b, v197
; __device__ __forceinline__ unsigned cvt_pk_bf16(float lo, float hi) { unsigned r; asm volatile("v_cvt_pk_bf16_f32 %0, %1, %2" : "=v"(r) : "v"(lo), "v"(hi)); return r; }
;     __device__ __forceinline__ void operator()(const f32x4 (&acc)[2][2][4][2], const Unit& u, int wr, int wc, int fr, int fq) const {
;     ...
;             for (int m = 0; m < 4; ++m) { const int row = row0 + ai * HALF + m * 16; const float rs = __builtin_amdgcn_rsqf((float)sq[ai][m] * (1.0f / (1024.0f * 1048576.0f)) + RMS_EPS);
;                 float hv[8];
; #pragma unroll
;                 for (int n = 0; n < 2; ++n)
; #pragma unroll
;                     for (int j = 0; j < 4; ++j) { const float g = acc[ai][0][m][n][j] * rs, uu = acc[ai][1][m][n][j] * rs;
;                         const float sg = g * __builtin_amdgcn_rcpf(1.0f + __builtin_amdgcn_exp2f(-1.4426950408889634f * g)); hv[n * 4 + j] = sg * uu; }
;                 u32x4 w; w.x = cvt_pk_bf16(hv[0], hv[1]); w.y = cvt_pk_bf16(hv[2], hv[3]); w.z = cvt_pk_bf16(hv[4], hv[5]); w.w = cvt_pk_bf16(hv[6], hv[7]);
;                 *(u32x4*)(H + (size_t)row * 2816 + col0) = w; }
	v_mul_f32_e32 v214, 0xbfb8aa3b, v198
	v_mul_f32_e32 v215, 0xbfb8aa3b, v199
	v_mul_f32_e32 v216, 0xbfb8aa3b, v200
	v_mul_f32_e32 v217, 0xbfb8aa3b, v201
	v_mul_f32_e32 v218, 0xbfb8aa3b, v202
	v_mul_f32_e32 v219, 0xbfb8aa3b, v203
	v_exp_f32_e32 v212, v212
	v_exp_f32_e32 v213, v213
	v_exp_f32_e32 v214, v214
	v_exp_f32_e32 v215, v215
	v_exp_f32_e32 v216, v216
	v_exp_f32_e32 v217, v217
	v_exp_f32_e32 v218, v218
	v_exp_f32_e32 v219, v219
	v_add_f32_e32 v212, 1.0, v212
	v_add_f32_e32 v213, 1.0, v213
	v_add_f32_e32 v214, 1.0, v214
	v_add_f32_e32 v215, 1.0, v215
	v_add_f32_e32 v216, 1.0, v216
	v_add_f32_e32 v217, 1.0, v217
	v_add_f32_e32 v218, 1.0, v218
	v_add_f32_e32 v219, 1.0, v219
	v_rcp_f32_e32 v212, v212
	v_rcp_f32_e32 v213, v213
	v_rcp_f32_e32 v214, v214
	v_rcp_f32_e32 v215, v215
	v_rcp_f32_e32 v216, v216
	v_rcp_f32_e32 v217, v217
	v_rcp_f32_e32 v218, v218
	v_rcp_f32_e32 v219, v219
	v_mul_f32_e32 v212, v196, v212
	v_mul_f32_e32 v213, v197, v213
	v_mul_f32_e32 v214, v198, v214
	v_mul_f32_e32 v215, v199, v215
	v_mul_f32_e32 v216, v200, v216
	v_mul_f32_e32 v217, v201, v217
	v_mul_f32_e32 v218, v202, v218
	v_mul_f32_e32 v219, v203, v219
	v_mul_f32_e32 v212, v204, v212
	v_mul_f32_e32 v213, v205, v213
	v_mul_f32_e32 v214, v206, v214
	v_mul_f32_e32 v215, v207, v215
	v_mul_f32_e32 v216, v208, v216
	v_mul_f32_e32 v217, v209, v217
	v_mul_f32_e32 v218, v210, v218
	v_mul_f32_e32 v219, v211, v219
	v_mad_i64_i32 v[186:187], s[16:17], v148, s9, v[180:181]
	v_cvt_pk_bf16_f32 v192, v212, v213
	v_cvt_pk_bf16_f32 v193, v214, v215
	v_cvt_pk_bf16_f32 v194, v216, v217
	v_cvt_pk_bf16_f32 v195, v218, v219
	v_lshl_add_u64 v[186:187], v[186:187], 0, v[182:183]
	global_store_dwordx4 v[186:187], v[192:195], off
	v_mul_f32_e32 v196, v62, v176
	v_mul_f32_e32 v197, v63, v176
	v_mul_f32_e32 v198, v64, v176
	v_mul_f32_e32 v199, v65, v176
	v_mul_f32_e32 v200, v54, v176
	v_mul_f32_e32 v201, v55, v176
	v_mul_f32_e32 v202, v56, v176
	v_mul_f32_e32 v203, v57, v176
	v_mul_f32_e32 v204, v58, v176
	v_mul_f32_e32 v205, v59, v176
	v_mul_f32_e32 v206, v60, v176
	v_mul_f32_e32 v207, v61, v176
	v_mul_f32_e32 v208, v50, v176
	v_mul_f32_e32 v209, v51, v176
	v_mul_f32_e32 v210, v52, v176
	v_mul_f32_e32 v211, v53, v176
	v_mul_f32_e32 v212, 0xbfb8aa3b, v196
	v_mul_f32_e32 v213, 0xbfb8aa3b, v197
	v_mul_f32_e32 v214, 0xbfb8aa3b, v198
	v_mul_f32_e32 v215, 0xbfb8aa3b, v199
	v_mul_f32_e32 v216, 0xbfb8aa3b, v200
	v_mul_f32_e32 v217, 0xbfb8aa3b, v201
	v_mul_f32_e32 v218, 0xbfb8aa3b, v202
	v_mul_f32_e32 v219, 0xbfb8aa3b, v203
	v_exp_f32_e32 v212, v212
	v_exp_f32_e32 v213, v213
	v_exp_f32_e32 v214, v214
	v_exp_f32_e32 v215, v215
	v_exp_f32_e32 v216, v216
	v_exp_f32_e32 v217, v217
	v_exp_f32_e32 v218, v218
	v_exp_f32_e32 v219, v219
	v_add_f32_e32 v212, 1.0, v212
	v_add_f32_e32 v213, 1.0, v213
	v_add_f32_e32 v214, 1.0, v214
	v_add_f32_e32 v215, 1.0, v215
	v_add_f32_e32 v216, 1.0, v216
	v_add_f32_e32 v217, 1.0, v217
	v_add_f32_e32 v218, 1.0, v218
	v_add_f32_e32 v219, 1.0, v219
	v_rcp_f32_e32 v212, v212
	v_rcp_f32_e32 v213, v213
	v_rcp_f32_e32 v214, v214
	v_rcp_f32_e32 v215, v215
	v_rcp_f32_e32 v216, v216
	v_rcp_f32_e32 v217, v217
	v_rcp_f32_e32 v218, v218
	v_rcp_f32_e32 v219, v219
	v_mul_f32_e32 v212, v196, v212
	v_mul_f32_e32 v213, v197, v213
	v_mul_f32_e32 v214, v198, v214
	v_mul_f32_e32 v215, v199, v215
	v_mul_f32_e32 v216, v200, v216
	v_mul_f32_e32 v217, v201, v217
	v_mul_f32_e32 v218, v202, v218
	v_mul_f32_e32 v219, v203, v219
	v_mul_f32_e32 v212, v204, v212
	v_mul_f32_e32 v213, v205, v213
	v_mul_f32_e32 v214, v206, v214
	v_mul_f32_e32 v215, v207, v215
	v_mul_f32_e32 v216, v208, v216
	v_mul_f32_e32 v217, v209, v217
	v_mul_f32_e32 v218, v210, v218
	v_mul_f32_e32 v219, v211, v219
	v_mad_i64_i32 v[184:185], s[16:17], v161, s9, v[180:181]
	v_cvt_pk_bf16_f32 v188, v212, v213
	v_cvt_pk_bf16_f32 v189, v214, v215
	v_cvt_pk_bf16_f32 v190, v216, v217
	v_cvt_pk_bf16_f32 v191, v218, v219
	v_lshl_add_u64 v[184:185], v[184:185], 0, v[182:183]
	global_store_dwordx4 v[184:185], v[188:191], off
	v_mul_f32_e32 v196, v46, v177
	v_mul_f32_e32 v197, v47, v177
	v_mul_f32_e32 v198, v48, v177
	v_mul_f32_e32 v199, v49, v177
	v_mul_f32_e32 v200, v38, v177
	v_mul_f32_e32 v201, v39, v177
	v_mul_f32_e32 v202, v40, v177
	v_mul_f32_e32 v203, v41, v177
	v_mul_f32_e32 v204, v42, v177
	v_mul_f32_e32 v205, v43, v177
	v_mul_f32_e32 v206, v44, v177
	v_mul_f32_e32 v207, v45, v177
	v_mul_f32_e32 v208, v34, v177
	v_mul_f32_e32 v209, v35, v177
	v_mul_f32_e32 v210, v36, v177
	v_mul_f32_e32 v211, v37, v177
	v_mul_f32_e32 v212, 0xbfb8aa3b, v196
	v_mul_f32_e32 v213, 0xbfb8aa3b, v197
	v_mul_f32_e32 v214, 0xbfb8aa3b, v198
	v_mul_f32_e32 v215, 0xbfb8aa3b, v199
	v_mul_f32_e32 v216, 0xbfb8aa3b, v200
	v_mul_f32_e32 v217, 0xbfb8aa3b, v201
	v_mul_f32_e32 v218, 0xbfb8aa3b, v202
	v_mul_f32_e32 v219, 0xbfb8aa3b, v203
	v_exp_f32_e32 v212, v212
	v_exp_f32_e32 v213, v213
	v_exp_f32_e32 v214, v214
	v_exp_f32_e32 v215, v215
	v_exp_f32_e32 v216, v216
	v_exp_f32_e32 v217, v217
	v_exp_f32_e32 v218, v218
	v_exp_f32_e32 v219, v219
	v_add_f32_e32 v212, 1.0, v212
	v_add_f32_e32 v213, 1.0, v213
	v_add_f32_e32 v214, 1.0, v214
	v_add_f32_e32 v215, 1.0, v215
	v_add_f32_e32 v216, 1.0, v216
	v_add_f32_e32 v217, 1.0, v217
	v_add_f32_e32 v218, 1.0, v218
	v_add_f32_e32 v219, 1.0, v219
	v_rcp_f32_e32 v212, v212
	v_rcp_f32_e32 v213, v213
	v_rcp_f32_e32 v214, v214
	v_rcp_f32_e32 v215, v215
	v_rcp_f32_e32 v216, v216
	v_rcp_f32_e32 v217, v217
	v_rcp_f32_e32 v218, v218
	v_rcp_f32_e32 v219, v219
	v_mul_f32_e32 v212, v196, v212
; __device__ __forceinline__ unsigned cvt_pk_bf16(float lo, float hi) { unsigned r; asm volatile("v_cvt_pk_bf16_f32 %0, %1, %2" : "=v"(r) : "v"(lo), "v"(hi)); return r; }
; #define PG8_BAR __builtin_amdgcn_s_barrier()
;     __device__ __forceinline__ void operator()(const f32x4 (&acc)[2][2][4][2], const Unit& u, int wr, int wc, int fr, int fq) const {
;     ...
;             for (int m = 0; m < 4; ++m) { const int row = row0 + ai * HALF + m * 16; const float rs = __builtin_amdgcn_rsqf((float)sq[ai][m] * (1.0f / (1024.0f * 1048576.0f)) + RMS_EPS);
;                 float hv[8];
; #pragma unroll
;                 for (int n = 0; n < 2; ++n)
; #pragma unroll
;                     for (int j = 0; j < 4; ++j) { const float g = acc[ai][0][m][n][j] * rs, uu = acc[ai][1][m][n][j] * rs;
;                         const float sg = g * __builtin_amdgcn_rcpf(1.0f + __builtin_amdgcn_exp2f(-1.4426950408889634f * g)); hv[n * 4 + j] = sg * uu; }
;                 u32x4 w; w.x = cvt_pk_bf16(hv[0], hv[1]); w.y = cvt_pk_bf16(hv[2], hv[3]); w.z = cvt_pk_bf16(hv[4], hv[5]); w.w = cvt_pk_bf16(hv[6], hv[7]);
;                 *(u32x4*)(H + (size_t)row * 2816 + col0) = w; }
; template <class Epi, class Sched, bool ALIGN_EPI = false, bool SP2 = false>
; __device__ __forceinline__ void gemm_phase(PG8_LAS unsigned char* lds, const Gemm g, const Sched& S, const Epi& E, const int wv) {
;     ...
;         if constexpr (!Epi::AFTER_DRAIN) { E(acc, cur, wr, wc, fr, fq); S.done(cur); }
;         if (!has_next) break;
; #pragma unroll
;         for (int a = 0; a < 2; ++a)
; #pragma unroll
;             for (int b = 0; b < 2; ++b)
; #pragma unroll
;                 for (int m = 0; m < 4; ++m)
; #pragma unroll
;                     for (int n = 0; n < 2; ++n) acc[a][b][m][n] = (f32x4){0.f, 0.f, 0.f, 0.f};
;         cur = nxt; cA = nA; cB = nB; ++ui;
;         if constexpr (ALIGN_EPI) { if (wr == 1) PG8_BAR; }
	v_mul_f32_e32 v213, v197, v213
	v_mul_f32_e32 v214, v198, v214
	v_mul_f32_e32 v215, v199, v215
	v_mul_f32_e32 v216, v200, v216
	v_mul_f32_e32 v217, v201, v217
	v_mul_f32_e32 v218, v202, v218
	v_mul_f32_e32 v219, v203, v219
	v_mul_f32_e32 v212, v204, v212
	v_mul_f32_e32 v213, v205, v213
	v_mul_f32_e32 v214, v206, v214
	v_mul_f32_e32 v215, v207, v215
	v_mul_f32_e32 v216, v208, v216
	v_mul_f32_e32 v217, v209, v217
	v_mul_f32_e32 v218, v210, v218
	v_mul_f32_e32 v219, v211, v219
	v_mad_i64_i32 v[186:187], s[16:17], v157, s9, v[180:181]
	v_cvt_pk_bf16_f32 v192, v212, v213
	v_cvt_pk_bf16_f32 v193, v214, v215
	v_cvt_pk_bf16_f32 v194, v216, v217
	v_cvt_pk_bf16_f32 v195, v218, v219
	v_lshl_add_u64 v[186:187], v[186:187], 0, v[182:183]
	global_store_dwordx4 v[186:187], v[192:195], off
	v_mul_f32_e32 v196, v30, v178
	v_mul_f32_e32 v197, v31, v178
	v_mul_f32_e32 v198, v32, v178
	v_mul_f32_e32 v199, v33, v178
	v_mul_f32_e32 v200, v22, v178
	v_mul_f32_e32 v201, v23, v178
	v_mul_f32_e32 v202, v24, v178
	v_mul_f32_e32 v203, v25, v178
	v_mul_f32_e32 v204, v26, v178
	v_mul_f32_e32 v205, v27, v178
	v_mul_f32_e32 v206, v28, v178
	v_mul_f32_e32 v207, v29, v178
	v_mul_f32_e32 v208, v18, v178
	v_mul_f32_e32 v209, v19, v178
	v_mul_f32_e32 v210, v20, v178
	v_mul_f32_e32 v211, v21, v178
	v_mul_f32_e32 v212, 0xbfb8aa3b, v196
	v_mul_f32_e32 v213, 0xbfb8aa3b, v197
	v_mul_f32_e32 v214, 0xbfb8aa3b, v198
	v_mul_f32_e32 v215, 0xbfb8aa3b, v199
	v_mul_f32_e32 v216, 0xbfb8aa3b, v200
	v_mul_f32_e32 v217, 0xbfb8aa3b, v201
	v_mul_f32_e32 v218, 0xbfb8aa3b, v202
	v_mul_f32_e32 v219, 0xbfb8aa3b, v203
	v_exp_f32_e32 v212, v212
	v_exp_f32_e32 v213, v213
	v_exp_f32_e32 v214, v214
	v_exp_f32_e32 v215, v215
	v_exp_f32_e32 v216, v216
	v_exp_f32_e32 v217, v217
	v_exp_f32_e32 v218, v218
	v_exp_f32_e32 v219, v219
	v_add_f32_e32 v212, 1.0, v212
	v_add_f32_e32 v213, 1.0, v213
	v_add_f32_e32 v214, 1.0, v214
	v_add_f32_e32 v215, 1.0, v215
	v_add_f32_e32 v216, 1.0, v216
	v_add_f32_e32 v217, 1.0, v217
	v_add_f32_e32 v218, 1.0, v218
	v_add_f32_e32 v219, 1.0, v219
	v_rcp_f32_e32 v212, v212
	v_rcp_f32_e32 v213, v213
	v_rcp_f32_e32 v214, v214
	v_rcp_f32_e32 v215, v215
	v_rcp_f32_e32 v216, v216
	v_rcp_f32_e32 v217, v217
	v_rcp_f32_e32 v218, v218
	v_rcp_f32_e32 v219, v219
	v_mul_f32_e32 v212, v196, v212
	v_mul_f32_e32 v213, v197, v213
	v_mul_f32_e32 v214, v198, v214
	v_mul_f32_e32 v215, v199, v215
	v_mul_f32_e32 v216, v200, v216
	v_mul_f32_e32 v217, v201, v217
	v_mul_f32_e32 v218, v202, v218
	v_mul_f32_e32 v219, v203, v219
	v_mul_f32_e32 v212, v204, v212
	v_mul_f32_e32 v213, v205, v213
	v_mul_f32_e32 v214, v206, v214
	v_mul_f32_e32 v215, v207, v215
	v_mul_f32_e32 v216, v208, v216
	v_mul_f32_e32 v217, v209, v217
	v_mul_f32_e32 v218, v210, v218
	v_mul_f32_e32 v219, v211, v219
	v_mad_i64_i32 v[184:185], s[16:17], v153, s9, v[180:181]
	v_cvt_pk_bf16_f32 v188, v212, v213
	v_cvt_pk_bf16_f32 v189, v214, v215
	v_cvt_pk_bf16_f32 v190, v216, v217
	v_cvt_pk_bf16_f32 v191, v218, v219
	v_lshl_add_u64 v[184:185], v[184:185], 0, v[182:183]
	global_store_dwordx4 v[184:185], v[188:191], off
	v_mul_f32_e32 v196, v14, v179
	v_mul_f32_e32 v197, v15, v179
	v_mul_f32_e32 v198, v16, v179
	v_mul_f32_e32 v199, v17, v179
	v_mul_f32_e32 v200, v6, v179
	v_mul_f32_e32 v201, v7, v179
	v_mul_f32_e32 v202, v8, v179
	v_mul_f32_e32 v203, v9, v179
	v_mul_f32_e32 v204, v10, v179
	v_mul_f32_e32 v205, v11, v179
	v_mul_f32_e32 v206, v12, v179
	v_mul_f32_e32 v207, v13, v179
	v_mul_f32_e32 v208, v2, v179
	v_mul_f32_e32 v209, v3, v179
	v_mul_f32_e32 v210, v4, v179
	v_mul_f32_e32 v211, v5, v179
	v_mul_f32_e32 v212, 0xbfb8aa3b, v196
	v_mul_f32_e32 v213, 0xbfb8aa3b, v197
	v_mul_f32_e32 v214, 0xbfb8aa3b, v198
	v_mul_f32_e32 v215, 0xbfb8aa3b, v199
	v_mul_f32_e32 v216, 0xbfb8aa3b, v200
	v_mul_f32_e32 v217, 0xbfb8aa3b, v201
	v_mul_f32_e32 v218, 0xbfb8aa3b, v202
	v_mul_f32_e32 v219, 0xbfb8aa3b, v203
	v_exp_f32_e32 v212, v212
	v_exp_f32_e32 v213, v213
	v_exp_f32_e32 v214, v214
	v_exp_f32_e32 v215, v215
	v_exp_f32_e32 v216, v216
	v_exp_f32_e32 v217, v217
	v_exp_f32_e32 v218, v218
	v_exp_f32_e32 v219, v219
	v_add_f32_e32 v212, 1.0, v212
	v_add_f32_e32 v213, 1.0, v213
	v_add_f32_e32 v214, 1.0, v214
	v_add_f32_e32 v215, 1.0, v215
	v_add_f32_e32 v216, 1.0, v216
	v_add_f32_e32 v217, 1.0, v217
	v_add_f32_e32 v218, 1.0, v218
	v_add_f32_e32 v219, 1.0, v219
	v_rcp_f32_e32 v212, v212
	v_rcp_f32_e32 v213, v213
	v_rcp_f32_e32 v214, v214
	v_rcp_f32_e32 v215, v215
	v_rcp_f32_e32 v216, v216
	v_rcp_f32_e32 v217, v217
	v_rcp_f32_e32 v218, v218
	v_rcp_f32_e32 v219, v219
	v_mul_f32_e32 v212, v196, v212
	v_mul_f32_e32 v213, v197, v213
	v_mul_f32_e32 v214, v198, v214
	v_mul_f32_e32 v215, v199, v215
	v_mul_f32_e32 v216, v200, v216
	v_mul_f32_e32 v217, v201, v217
	v_mul_f32_e32 v218, v202, v218
	v_mul_f32_e32 v219, v203, v219
	v_mul_f32_e32 v212, v204, v212
	v_mul_f32_e32 v213, v205, v213
	v_mul_f32_e32 v214, v206, v214
	v_mul_f32_e32 v215, v207, v215
	v_mul_f32_e32 v216, v208, v216
	v_mul_f32_e32 v217, v209, v217
	v_mul_f32_e32 v218, v210, v218
	v_mul_f32_e32 v219, v211, v219
	v_mad_i64_i32 v[186:187], s[16:17], v149, s9, v[180:181]
	v_cvt_pk_bf16_f32 v192, v212, v213
	v_cvt_pk_bf16_f32 v193, v214, v215
	v_cvt_pk_bf16_f32 v194, v216, v217
	v_cvt_pk_bf16_f32 v195, v218, v219
	v_lshl_add_u64 v[186:187], v[186:187], 0, v[182:183]
	s_mov_b64 s[16:17], -1
	global_store_dwordx4 v[186:187], v[192:195], off
	s_cbranch_vccnz .LBB0_424
	s_andn2_b64 vcc, exec, s[0:1]
	s_cbranch_vccnz .LBB0_423
	s_barrier
	s_branch .LBB0_423
